# v35: v34 + layer-B projection z-tile epilogue also takes its eight rinv rows from the in-loop prefetch (no loads in that path)
# baseline (speedup 1.0000x reference)
.LBB0_162:
	v_lshl_add_u64 v[134:135], v[152:153], 2, s[16:17]
	v_lshl_add_u32 v132, s48, 8, v177
	v_mov_b32_e32 v133, v2
	v_lshlrev_b64 v[160:161], 11, v[152:153]
	v_lshl_add_u64 v[162:163], s[14:15], 0, v[160:161]
	v_lshlrev_b64 v[160:161], 1, v[132:133]
	v_lshl_add_u64 v[132:133], v[162:163], 0, v[160:161]
	v_ashrrev_i32_e32 v159, 31, v158
	v_ashrrev_i32_e32 v157, 31, v156
	v_ashrrev_i32_e32 v155, 31, v154
	s_mov_b64 s[0:1], 0x40000
	s_waitcnt vmcnt(0)
	v_mov_b32_e32 v166, v228
	v_pk_mul_f32 v[164:165], v[128:129], v[166:167] op_sel_hi:[1,0]
	s_nop 0
	v_mul_f32_e32 v151, 0xbfb8aa3b, v164
	v_exp_f32_e32 v151, v151
	v_pk_mul_f32 v[162:163], v[130:131], v[166:167] op_sel_hi:[1,0]
	v_pk_mul_f32 v[170:171], v[124:125], v[166:167] op_sel_hi:[1,0]
	v_add_f32_e32 v151, 1.0, v151
	v_rcp_f32_e32 v168, v151
	v_mul_f32_e32 v151, 0xbfb8aa3b, v165
	v_exp_f32_e32 v151, v151
	s_nop 0
	v_add_f32_e32 v151, 1.0, v151
	v_rcp_f32_e32 v169, v151
	v_mul_f32_e32 v151, 0xbfb8aa3b, v162
	v_exp_f32_e32 v151, v151
	v_pk_mul_f32 v[164:165], v[164:165], v[168:169]
	v_add_f32_e32 v151, 1.0, v151
	v_rcp_f32_e32 v168, v151
	v_mul_f32_e32 v151, 0xbfb8aa3b, v163
	v_exp_f32_e32 v151, v151
	s_nop 0
	v_add_f32_e32 v151, 1.0, v151
	v_rcp_f32_e32 v169, v151
	v_mul_f32_e32 v151, 0xbfb8aa3b, v170
	v_exp_f32_e32 v151, v151
	v_pk_mul_f32 v[168:169], v[162:163], v[168:169]
	v_pk_mul_f32 v[162:163], v[126:127], v[166:167] op_sel_hi:[1,0]
	v_add_f32_e32 v151, 1.0, v151
	v_rcp_f32_e32 v172, v151
	v_mul_f32_e32 v151, 0xbfb8aa3b, v171
	v_exp_f32_e32 v151, v151
	s_nop 0
	v_add_f32_e32 v151, 1.0, v151
	v_rcp_f32_e32 v173, v151
	v_mul_f32_e32 v151, 0xbfb8aa3b, v162
	v_exp_f32_e32 v151, v151
	v_pk_mul_f32 v[170:171], v[170:171], v[172:173]
	v_add_f32_e32 v151, 1.0, v151
	v_rcp_f32_e32 v172, v151
	v_mul_f32_e32 v151, 0xbfb8aa3b, v163
	v_exp_f32_e32 v151, v151
	s_nop 0
	v_add_f32_e32 v151, 1.0, v151
	v_rcp_f32_e32 v173, v151
	s_nop 0
	v_pk_mul_f32 v[172:173], v[162:163], v[172:173]
	v_cvt_pk_bf16_f32 v162, v164, v165
	v_cvt_pk_bf16_f32 v163, v168, v169
	v_cvt_pk_bf16_f32 v164, v170, v171
	v_cvt_pk_bf16_f32 v165, v172, v173
	global_store_dwordx4 v[132:133], v[162:165], off
	s_nop 1
	v_pk_mul_f32 v[162:163], v[120:121], v[166:167] op_sel_hi:[1,0]
	v_pk_mul_f32 v[164:165], v[122:123], v[166:167] op_sel_hi:[1,0]
	v_mul_f32_e32 v151, 0xbfb8aa3b, v162
	v_exp_f32_e32 v151, v151
	s_nop 0
	v_add_f32_e32 v151, 1.0, v151
	v_rcp_f32_e32 v168, v151
	v_mul_f32_e32 v151, 0xbfb8aa3b, v163
	v_exp_f32_e32 v151, v151
	s_nop 0
	v_add_f32_e32 v151, 1.0, v151
	v_rcp_f32_e32 v169, v151
	v_mul_f32_e32 v151, 0xbfb8aa3b, v164
	v_exp_f32_e32 v151, v151
	v_pk_mul_f32 v[162:163], v[162:163], v[168:169]
	s_nop 0
	v_cvt_pk_bf16_f32 v162, v162, v163
	v_add_f32_e32 v151, 1.0, v151
	v_rcp_f32_e32 v168, v151
	v_mul_f32_e32 v151, 0xbfb8aa3b, v165
	v_exp_f32_e32 v151, v151
	s_nop 0
	v_add_f32_e32 v151, 1.0, v151
	v_rcp_f32_e32 v169, v151
	s_nop 0
	v_pk_mul_f32 v[164:165], v[164:165], v[168:169]
	v_pk_mul_f32 v[168:169], v[118:119], v[166:167] op_sel_hi:[1,0]
	v_pk_mul_f32 v[166:167], v[116:117], v[166:167] op_sel_hi:[1,0]
	v_cvt_pk_bf16_f32 v163, v164, v165
	v_mul_f32_e32 v151, 0xbfb8aa3b, v166
	v_exp_f32_e32 v151, v151
	s_nop 0
	v_add_f32_e32 v151, 1.0, v151
	v_rcp_f32_e32 v170, v151
	v_mul_f32_e32 v151, 0xbfb8aa3b, v167
	v_exp_f32_e32 v151, v151
	s_nop 0
	v_add_f32_e32 v151, 1.0, v151
	v_rcp_f32_e32 v171, v151
	v_mul_f32_e32 v151, 0xbfb8aa3b, v168
	v_exp_f32_e32 v151, v151
	v_pk_mul_f32 v[166:167], v[166:167], v[170:171]
	s_nop 0
	v_cvt_pk_bf16_f32 v164, v166, v167
	v_add_f32_e32 v151, 1.0, v151
	v_rcp_f32_e32 v170, v151
	v_mul_f32_e32 v151, 0xbfb8aa3b, v169
	v_exp_f32_e32 v151, v151
	s_nop 0
	v_add_f32_e32 v151, 1.0, v151
	v_rcp_f32_e32 v171, v151
	s_nop 0
	v_pk_mul_f32 v[168:169], v[168:169], v[170:171]
	s_nop 0
	v_cvt_pk_bf16_f32 v165, v168, v169
	global_store_dwordx4 v[132:133], v[162:165], off offset:256
	s_nop 1
	v_mov_b32_e32 v168, v229
	v_pk_mul_f32 v[166:167], v[112:113], v[168:169] op_sel_hi:[1,0]
	s_nop 0
	v_mul_f32_e32 v151, 0xbfb8aa3b, v166
	v_exp_f32_e32 v151, v151
	v_pk_mul_f32 v[164:165], v[114:115], v[168:169] op_sel_hi:[1,0]
	v_pk_mul_f32 v[172:173], v[108:109], v[168:169] op_sel_hi:[1,0]
	v_lshlrev_b64 v[162:163], 11, v[158:159]
	v_add_f32_e32 v151, 1.0, v151
	v_rcp_f32_e32 v170, v151
	v_mul_f32_e32 v151, 0xbfb8aa3b, v167
	v_exp_f32_e32 v151, v151
	v_lshl_add_u64 v[162:163], s[14:15], 0, v[162:163]
	v_lshl_add_u64 v[162:163], v[162:163], 0, v[160:161]
	v_add_f32_e32 v151, 1.0, v151
	v_rcp_f32_e32 v171, v151
	v_mul_f32_e32 v151, 0xbfb8aa3b, v164
	v_exp_f32_e32 v151, v151
	v_pk_mul_f32 v[166:167], v[166:167], v[170:171]
	v_add_f32_e32 v151, 1.0, v151
	v_rcp_f32_e32 v170, v151
	v_mul_f32_e32 v151, 0xbfb8aa3b, v165
	v_exp_f32_e32 v151, v151
	s_nop 0
	v_add_f32_e32 v151, 1.0, v151
	v_rcp_f32_e32 v171, v151
	v_mul_f32_e32 v151, 0xbfb8aa3b, v172
	v_exp_f32_e32 v151, v151
	v_pk_mul_f32 v[170:171], v[164:165], v[170:171]
	v_pk_mul_f32 v[164:165], v[110:111], v[168:169] op_sel_hi:[1,0]
	v_add_f32_e32 v151, 1.0, v151
	v_rcp_f32_e32 v174, v151
	v_mul_f32_e32 v151, 0xbfb8aa3b, v173
	v_exp_f32_e32 v151, v151
	s_nop 0
	v_add_f32_e32 v151, 1.0, v151
	v_rcp_f32_e32 v175, v151
	v_mul_f32_e32 v151, 0xbfb8aa3b, v164
	v_exp_f32_e32 v151, v151
	v_pk_mul_f32 v[172:173], v[172:173], v[174:175]
	v_add_f32_e32 v151, 1.0, v151
	v_rcp_f32_e32 v174, v151
	v_mul_f32_e32 v151, 0xbfb8aa3b, v165
	v_exp_f32_e32 v151, v151
	s_nop 0
	v_add_f32_e32 v151, 1.0, v151
	v_rcp_f32_e32 v175, v151
	s_nop 0
	v_pk_mul_f32 v[174:175], v[164:165], v[174:175]
	v_cvt_pk_bf16_f32 v164, v166, v167
	v_cvt_pk_bf16_f32 v165, v170, v171
	v_cvt_pk_bf16_f32 v166, v172, v173
	v_cvt_pk_bf16_f32 v167, v174, v175
	global_store_dwordx4 v[162:163], v[164:167], off
	s_nop 1
	v_pk_mul_f32 v[164:165], v[104:105], v[168:169] op_sel_hi:[1,0]
	v_pk_mul_f32 v[166:167], v[106:107], v[168:169] op_sel_hi:[1,0]
	v_mul_f32_e32 v151, 0xbfb8aa3b, v164
	v_exp_f32_e32 v151, v151
	s_nop 0
	v_add_f32_e32 v151, 1.0, v151
	v_rcp_f32_e32 v170, v151
	v_mul_f32_e32 v151, 0xbfb8aa3b, v165
	v_exp_f32_e32 v151, v151
	s_nop 0
	v_add_f32_e32 v151, 1.0, v151
	v_rcp_f32_e32 v171, v151
	v_mul_f32_e32 v151, 0xbfb8aa3b, v166
	v_exp_f32_e32 v151, v151
	v_pk_mul_f32 v[164:165], v[164:165], v[170:171]
	s_nop 0
	v_cvt_pk_bf16_f32 v164, v164, v165
	v_add_f32_e32 v151, 1.0, v151
	v_rcp_f32_e32 v170, v151
	v_mul_f32_e32 v151, 0xbfb8aa3b, v167
	v_exp_f32_e32 v151, v151
	s_nop 0
	v_add_f32_e32 v151, 1.0, v151
	v_rcp_f32_e32 v171, v151
	s_nop 0
	v_pk_mul_f32 v[166:167], v[166:167], v[170:171]
	v_pk_mul_f32 v[170:171], v[102:103], v[168:169] op_sel_hi:[1,0]
	v_pk_mul_f32 v[168:169], v[100:101], v[168:169] op_sel_hi:[1,0]
	v_cvt_pk_bf16_f32 v165, v166, v167
	v_mul_f32_e32 v151, 0xbfb8aa3b, v168
	v_exp_f32_e32 v151, v151
	s_nop 0
	v_add_f32_e32 v151, 1.0, v151
	v_rcp_f32_e32 v172, v151
	v_mul_f32_e32 v151, 0xbfb8aa3b, v169
	v_exp_f32_e32 v151, v151
	s_nop 0
	v_add_f32_e32 v151, 1.0, v151
	v_rcp_f32_e32 v173, v151
	v_mul_f32_e32 v151, 0xbfb8aa3b, v170
	v_exp_f32_e32 v151, v151
	v_pk_mul_f32 v[168:169], v[168:169], v[172:173]
	s_nop 0
	v_cvt_pk_bf16_f32 v166, v168, v169
	v_add_f32_e32 v151, 1.0, v151
	v_rcp_f32_e32 v172, v151
	v_mul_f32_e32 v151, 0xbfb8aa3b, v171
	v_exp_f32_e32 v151, v151
	s_nop 0
	v_add_f32_e32 v151, 1.0, v151
	v_rcp_f32_e32 v173, v151
	s_nop 0
	v_pk_mul_f32 v[170:171], v[170:171], v[172:173]
	s_nop 0
	v_cvt_pk_bf16_f32 v167, v170, v171
	global_store_dwordx4 v[162:163], v[164:167], off offset:256
	s_nop 1
	v_mov_b32_e32 v168, v244
	v_lshlrev_b64 v[162:163], 11, v[156:157]
	v_lshl_add_u64 v[162:163], s[14:15], 0, v[162:163]
	v_lshl_add_u64 v[162:163], v[162:163], 0, v[160:161]
	v_pk_mul_f32 v[166:167], v[96:97], v[168:169] op_sel_hi:[1,0]
	s_nop 0
	v_mul_f32_e32 v151, 0xbfb8aa3b, v166
	v_exp_f32_e32 v151, v151
	v_pk_mul_f32 v[164:165], v[98:99], v[168:169] op_sel_hi:[1,0]
	v_pk_mul_f32 v[172:173], v[92:93], v[168:169] op_sel_hi:[1,0]
	v_add_f32_e32 v151, 1.0, v151
	v_rcp_f32_e32 v170, v151
	v_mul_f32_e32 v151, 0xbfb8aa3b, v167
	v_exp_f32_e32 v151, v151
	s_nop 0
	v_add_f32_e32 v151, 1.0, v151
	v_rcp_f32_e32 v171, v151
	v_mul_f32_e32 v151, 0xbfb8aa3b, v164
	v_exp_f32_e32 v151, v151
	v_pk_mul_f32 v[166:167], v[166:167], v[170:171]
	v_add_f32_e32 v151, 1.0, v151
	v_rcp_f32_e32 v170, v151
	v_mul_f32_e32 v151, 0xbfb8aa3b, v165
	v_exp_f32_e32 v151, v151
	s_nop 0
	v_add_f32_e32 v151, 1.0, v151
	v_rcp_f32_e32 v171, v151
	v_mul_f32_e32 v151, 0xbfb8aa3b, v172
	v_exp_f32_e32 v151, v151
	v_pk_mul_f32 v[170:171], v[164:165], v[170:171]
	v_pk_mul_f32 v[164:165], v[94:95], v[168:169] op_sel_hi:[1,0]
	v_add_f32_e32 v151, 1.0, v151
	v_rcp_f32_e32 v174, v151
	v_mul_f32_e32 v151, 0xbfb8aa3b, v173
	v_exp_f32_e32 v151, v151
	s_nop 0
	v_add_f32_e32 v151, 1.0, v151
	v_rcp_f32_e32 v175, v151
	v_mul_f32_e32 v151, 0xbfb8aa3b, v164
	v_exp_f32_e32 v151, v151
	v_pk_mul_f32 v[172:173], v[172:173], v[174:175]
	v_add_f32_e32 v151, 1.0, v151
	v_rcp_f32_e32 v174, v151
	v_mul_f32_e32 v151, 0xbfb8aa3b, v165
	v_exp_f32_e32 v151, v151
	s_nop 0
	v_add_f32_e32 v151, 1.0, v151
	v_rcp_f32_e32 v175, v151
	s_nop 0
	v_pk_mul_f32 v[174:175], v[164:165], v[174:175]
	v_cvt_pk_bf16_f32 v164, v166, v167
	v_cvt_pk_bf16_f32 v165, v170, v171
	v_cvt_pk_bf16_f32 v166, v172, v173
	v_cvt_pk_bf16_f32 v167, v174, v175
	global_store_dwordx4 v[162:163], v[164:167], off
	s_nop 1
	v_pk_mul_f32 v[164:165], v[88:89], v[168:169] op_sel_hi:[1,0]
	v_pk_mul_f32 v[166:167], v[90:91], v[168:169] op_sel_hi:[1,0]
	v_mul_f32_e32 v151, 0xbfb8aa3b, v164
	v_exp_f32_e32 v151, v151
	s_nop 0
	v_add_f32_e32 v151, 1.0, v151
	v_rcp_f32_e32 v170, v151
	v_mul_f32_e32 v151, 0xbfb8aa3b, v165
	v_exp_f32_e32 v151, v151
	s_nop 0
	v_add_f32_e32 v151, 1.0, v151
	v_rcp_f32_e32 v171, v151
	v_mul_f32_e32 v151, 0xbfb8aa3b, v166
	v_exp_f32_e32 v151, v151
	v_pk_mul_f32 v[164:165], v[164:165], v[170:171]
	s_nop 0
	v_cvt_pk_bf16_f32 v164, v164, v165
	v_add_f32_e32 v151, 1.0, v151
	v_rcp_f32_e32 v170, v151
	v_mul_f32_e32 v151, 0xbfb8aa3b, v167
	v_exp_f32_e32 v151, v151
	s_nop 0
	v_add_f32_e32 v151, 1.0, v151
	v_rcp_f32_e32 v171, v151
	s_nop 0
	v_pk_mul_f32 v[166:167], v[166:167], v[170:171]
	v_pk_mul_f32 v[170:171], v[86:87], v[168:169] op_sel_hi:[1,0]
	v_pk_mul_f32 v[168:169], v[84:85], v[168:169] op_sel_hi:[1,0]
	v_cvt_pk_bf16_f32 v165, v166, v167
	v_mul_f32_e32 v151, 0xbfb8aa3b, v168
	v_exp_f32_e32 v151, v151
	s_nop 0
	v_add_f32_e32 v151, 1.0, v151
	v_rcp_f32_e32 v172, v151
	v_mul_f32_e32 v151, 0xbfb8aa3b, v169
	v_exp_f32_e32 v151, v151
	s_nop 0
	v_add_f32_e32 v151, 1.0, v151
	v_rcp_f32_e32 v173, v151
	v_mul_f32_e32 v151, 0xbfb8aa3b, v170
	v_exp_f32_e32 v151, v151
	v_pk_mul_f32 v[168:169], v[168:169], v[172:173]
	s_nop 0
	v_cvt_pk_bf16_f32 v166, v168, v169
	v_add_f32_e32 v151, 1.0, v151
	v_rcp_f32_e32 v172, v151
	v_mul_f32_e32 v151, 0xbfb8aa3b, v171
	v_exp_f32_e32 v151, v151
	s_nop 0
	v_add_f32_e32 v151, 1.0, v151
	v_rcp_f32_e32 v173, v151
	s_nop 0
	v_pk_mul_f32 v[170:171], v[170:171], v[172:173]
	s_nop 0
	v_cvt_pk_bf16_f32 v167, v170, v171
	global_store_dwordx4 v[162:163], v[164:167], off offset:256
	s_nop 1
	v_mov_b32_e32 v168, v245
	v_lshlrev_b64 v[162:163], 11, v[154:155]
	v_lshl_add_u64 v[162:163], s[14:15], 0, v[162:163]
	v_lshl_add_u64 v[160:161], v[162:163], 0, v[160:161]
	v_pk_mul_f32 v[164:165], v[80:81], v[168:169] op_sel_hi:[1,0]
	s_nop 0
	v_mul_f32_e32 v151, 0xbfb8aa3b, v164
	v_exp_f32_e32 v151, v151
	v_pk_mul_f32 v[162:163], v[82:83], v[168:169] op_sel_hi:[1,0]
	v_pk_mul_f32 v[170:171], v[76:77], v[168:169] op_sel_hi:[1,0]
	v_add_f32_e32 v151, 1.0, v151
	v_rcp_f32_e32 v166, v151
	v_mul_f32_e32 v151, 0xbfb8aa3b, v165
	v_exp_f32_e32 v151, v151
	s_nop 0
	v_add_f32_e32 v151, 1.0, v151
	v_rcp_f32_e32 v167, v151
	v_mul_f32_e32 v151, 0xbfb8aa3b, v162
	v_exp_f32_e32 v151, v151
	v_pk_mul_f32 v[164:165], v[164:165], v[166:167]
	v_add_f32_e32 v151, 1.0, v151
	v_rcp_f32_e32 v166, v151
	v_mul_f32_e32 v151, 0xbfb8aa3b, v163
	v_exp_f32_e32 v151, v151
	s_nop 0
	v_add_f32_e32 v151, 1.0, v151
	v_rcp_f32_e32 v167, v151
	v_mul_f32_e32 v151, 0xbfb8aa3b, v170
	v_exp_f32_e32 v151, v151
	v_pk_mul_f32 v[166:167], v[162:163], v[166:167]
	v_pk_mul_f32 v[162:163], v[78:79], v[168:169] op_sel_hi:[1,0]
	v_add_f32_e32 v151, 1.0, v151
	v_rcp_f32_e32 v172, v151
	v_mul_f32_e32 v151, 0xbfb8aa3b, v171
	v_exp_f32_e32 v151, v151
	s_nop 0
	v_add_f32_e32 v151, 1.0, v151
	v_rcp_f32_e32 v173, v151
	v_mul_f32_e32 v151, 0xbfb8aa3b, v162
	v_exp_f32_e32 v151, v151
	v_pk_mul_f32 v[170:171], v[170:171], v[172:173]
	v_add_f32_e32 v151, 1.0, v151
	v_rcp_f32_e32 v172, v151
	v_mul_f32_e32 v151, 0xbfb8aa3b, v163
	v_exp_f32_e32 v151, v151
	s_nop 0
	v_add_f32_e32 v151, 1.0, v151
	v_rcp_f32_e32 v173, v151
	s_nop 0
	v_pk_mul_f32 v[172:173], v[162:163], v[172:173]
	v_cvt_pk_bf16_f32 v162, v164, v165
	v_cvt_pk_bf16_f32 v163, v166, v167
	v_cvt_pk_bf16_f32 v164, v170, v171
	v_cvt_pk_bf16_f32 v165, v172, v173
	global_store_dwordx4 v[160:161], v[162:165], off
	s_nop 1
	v_pk_mul_f32 v[162:163], v[72:73], v[168:169] op_sel_hi:[1,0]
	v_pk_mul_f32 v[164:165], v[74:75], v[168:169] op_sel_hi:[1,0]
	v_mul_f32_e32 v151, 0xbfb8aa3b, v162
	v_exp_f32_e32 v151, v151
	s_nop 0
	v_add_f32_e32 v151, 1.0, v151
	v_rcp_f32_e32 v166, v151
	v_mul_f32_e32 v151, 0xbfb8aa3b, v163
	v_exp_f32_e32 v151, v151
	s_nop 0
	v_add_f32_e32 v151, 1.0, v151
	v_rcp_f32_e32 v167, v151
	v_mul_f32_e32 v151, 0xbfb8aa3b, v164
	v_exp_f32_e32 v151, v151
	v_pk_mul_f32 v[162:163], v[162:163], v[166:167]
	s_nop 0
	v_cvt_pk_bf16_f32 v162, v162, v163
	v_add_f32_e32 v151, 1.0, v151
	v_rcp_f32_e32 v166, v151
	v_mul_f32_e32 v151, 0xbfb8aa3b, v165
	v_exp_f32_e32 v151, v151
	s_nop 0
	v_add_f32_e32 v151, 1.0, v151
	v_rcp_f32_e32 v167, v151
	s_nop 0
	v_pk_mul_f32 v[164:165], v[164:165], v[166:167]
	v_pk_mul_f32 v[166:167], v[70:71], v[168:169] op_sel_hi:[1,0]
	v_pk_mul_f32 v[168:169], v[68:69], v[168:169] op_sel_hi:[1,0]
	v_cvt_pk_bf16_f32 v163, v164, v165
	v_mul_f32_e32 v151, 0xbfb8aa3b, v168
	v_exp_f32_e32 v151, v151
	s_nop 0
	v_add_f32_e32 v151, 1.0, v151
	v_rcp_f32_e32 v170, v151
	v_mul_f32_e32 v151, 0xbfb8aa3b, v169
	v_exp_f32_e32 v151, v151
	s_nop 0
	v_add_f32_e32 v151, 1.0, v151
	v_rcp_f32_e32 v171, v151
	v_mul_f32_e32 v151, 0xbfb8aa3b, v166
	v_exp_f32_e32 v151, v151
	v_pk_mul_f32 v[168:169], v[168:169], v[170:171]
	s_nop 0
	v_cvt_pk_bf16_f32 v164, v168, v169
	v_add_f32_e32 v151, 1.0, v151
	v_rcp_f32_e32 v170, v151
	v_mul_f32_e32 v151, 0xbfb8aa3b, v167
	v_exp_f32_e32 v151, v151
	s_nop 0
	v_add_f32_e32 v151, 1.0, v151
	v_rcp_f32_e32 v171, v151
	s_nop 0
	v_pk_mul_f32 v[166:167], v[166:167], v[170:171]
	s_nop 0
	v_cvt_pk_bf16_f32 v165, v166, v167
	global_store_dwordx4 v[160:161], v[162:165], off offset:256
	s_nop 1
	v_mov_b32_e32 v166, v246
	v_lshl_add_u64 v[160:161], v[132:133], 0, s[0:1]
	s_mov_b32 s0, 0x40000
	v_pk_mul_f32 v[164:165], v[64:65], v[166:167] op_sel_hi:[1,0]
	s_nop 0
	v_mul_f32_e32 v151, 0xbfb8aa3b, v164
	v_exp_f32_e32 v151, v151
	v_pk_mul_f32 v[162:163], v[66:67], v[166:167] op_sel_hi:[1,0]
	v_pk_mul_f32 v[170:171], v[60:61], v[166:167] op_sel_hi:[1,0]
	v_add_f32_e32 v151, 1.0, v151
	v_rcp_f32_e32 v168, v151
	v_mul_f32_e32 v151, 0xbfb8aa3b, v165
	v_exp_f32_e32 v151, v151
	s_nop 0
	v_add_f32_e32 v151, 1.0, v151
	v_rcp_f32_e32 v169, v151
	v_mul_f32_e32 v151, 0xbfb8aa3b, v162
	v_exp_f32_e32 v151, v151
	v_pk_mul_f32 v[164:165], v[164:165], v[168:169]
	v_add_f32_e32 v151, 1.0, v151
	v_rcp_f32_e32 v168, v151
	v_mul_f32_e32 v151, 0xbfb8aa3b, v163
	v_exp_f32_e32 v151, v151
	s_nop 0
	v_add_f32_e32 v151, 1.0, v151
	v_rcp_f32_e32 v169, v151
	v_mul_f32_e32 v151, 0xbfb8aa3b, v170
	v_exp_f32_e32 v151, v151
	v_pk_mul_f32 v[168:169], v[162:163], v[168:169]
	v_pk_mul_f32 v[162:163], v[62:63], v[166:167] op_sel_hi:[1,0]
	v_add_f32_e32 v151, 1.0, v151
	v_rcp_f32_e32 v172, v151
	v_mul_f32_e32 v151, 0xbfb8aa3b, v171
	v_exp_f32_e32 v151, v151
	s_nop 0
	v_add_f32_e32 v151, 1.0, v151
	v_rcp_f32_e32 v173, v151
	v_mul_f32_e32 v151, 0xbfb8aa3b, v162
	v_exp_f32_e32 v151, v151
	v_pk_mul_f32 v[170:171], v[170:171], v[172:173]
	v_add_f32_e32 v151, 1.0, v151
	v_rcp_f32_e32 v172, v151
	v_mul_f32_e32 v151, 0xbfb8aa3b, v163
	v_exp_f32_e32 v151, v151
	s_nop 0
	v_add_f32_e32 v151, 1.0, v151
	v_rcp_f32_e32 v173, v151
	s_nop 0
	v_pk_mul_f32 v[172:173], v[162:163], v[172:173]
	v_cvt_pk_bf16_f32 v163, v168, v169
	v_add_co_u32_e32 v168, vcc, s0, v132
	v_cvt_pk_bf16_f32 v162, v164, v165
	v_cvt_pk_bf16_f32 v164, v170, v171
	v_cvt_pk_bf16_f32 v165, v172, v173
	v_addc_co_u32_e32 v169, vcc, 0, v133, vcc
	global_store_dwordx4 v[168:169], v[162:165], off
	s_mov_b64 s[0:1], 0x48000
	s_nop 0
	v_pk_mul_f32 v[162:163], v[56:57], v[166:167] op_sel_hi:[1,0]
	v_pk_mul_f32 v[164:165], v[58:59], v[166:167] op_sel_hi:[1,0]
	v_mul_f32_e32 v151, 0xbfb8aa3b, v162
	v_exp_f32_e32 v151, v151
	s_nop 0
	v_add_f32_e32 v151, 1.0, v151
	v_rcp_f32_e32 v168, v151
	v_mul_f32_e32 v151, 0xbfb8aa3b, v163
	v_exp_f32_e32 v151, v151
	s_nop 0
	v_add_f32_e32 v151, 1.0, v151
	v_rcp_f32_e32 v169, v151
	v_mul_f32_e32 v151, 0xbfb8aa3b, v164
	v_exp_f32_e32 v151, v151
	v_pk_mul_f32 v[162:163], v[162:163], v[168:169]
	s_nop 0
	v_cvt_pk_bf16_f32 v162, v162, v163
	v_add_f32_e32 v151, 1.0, v151
	v_rcp_f32_e32 v168, v151
	v_mul_f32_e32 v151, 0xbfb8aa3b, v165
	v_exp_f32_e32 v151, v151
	s_nop 0
	v_add_f32_e32 v151, 1.0, v151
	v_rcp_f32_e32 v169, v151
	s_nop 0
	v_pk_mul_f32 v[164:165], v[164:165], v[168:169]
	v_pk_mul_f32 v[168:169], v[54:55], v[166:167] op_sel_hi:[1,0]
	v_pk_mul_f32 v[166:167], v[52:53], v[166:167] op_sel_hi:[1,0]
	v_cvt_pk_bf16_f32 v163, v164, v165
	v_mul_f32_e32 v151, 0xbfb8aa3b, v166
	v_exp_f32_e32 v151, v151
	s_nop 0
	v_add_f32_e32 v151, 1.0, v151
	v_rcp_f32_e32 v170, v151
	v_mul_f32_e32 v151, 0xbfb8aa3b, v167
	v_exp_f32_e32 v151, v151
	s_nop 0
	v_add_f32_e32 v151, 1.0, v151
	v_rcp_f32_e32 v171, v151
	v_mul_f32_e32 v151, 0xbfb8aa3b, v168
	v_exp_f32_e32 v151, v151
	v_pk_mul_f32 v[166:167], v[166:167], v[170:171]
	s_nop 0
	v_cvt_pk_bf16_f32 v164, v166, v167
	v_add_f32_e32 v151, 1.0, v151
	v_rcp_f32_e32 v170, v151
	v_mul_f32_e32 v151, 0xbfb8aa3b, v169
	v_exp_f32_e32 v151, v151
	s_nop 0
	v_add_f32_e32 v151, 1.0, v151
	v_rcp_f32_e32 v171, v151
	s_nop 0
	v_pk_mul_f32 v[168:169], v[168:169], v[170:171]
	s_nop 0
	v_cvt_pk_bf16_f32 v165, v168, v169
	global_store_dwordx4 v[160:161], v[162:165], off offset:256
	s_nop 1
	v_mov_b32_e32 v166, v248
	v_lshl_add_u64 v[160:161], v[132:133], 0, s[0:1]
	s_mov_b32 s0, 0x48000
	v_pk_mul_f32 v[164:165], v[48:49], v[166:167] op_sel_hi:[1,0]
	s_nop 0
	v_mul_f32_e32 v151, 0xbfb8aa3b, v164
	v_exp_f32_e32 v151, v151
	v_pk_mul_f32 v[162:163], v[50:51], v[166:167] op_sel_hi:[1,0]
	v_pk_mul_f32 v[170:171], v[44:45], v[166:167] op_sel_hi:[1,0]
	v_add_f32_e32 v151, 1.0, v151
	v_rcp_f32_e32 v168, v151
	v_mul_f32_e32 v151, 0xbfb8aa3b, v165
	v_exp_f32_e32 v151, v151
	s_nop 0
	v_add_f32_e32 v151, 1.0, v151
	v_rcp_f32_e32 v169, v151
	v_mul_f32_e32 v151, 0xbfb8aa3b, v162
	v_exp_f32_e32 v151, v151
	v_pk_mul_f32 v[164:165], v[164:165], v[168:169]
	v_add_f32_e32 v151, 1.0, v151
	v_rcp_f32_e32 v168, v151
	v_mul_f32_e32 v151, 0xbfb8aa3b, v163
	v_exp_f32_e32 v151, v151
	s_nop 0
	v_add_f32_e32 v151, 1.0, v151
	v_rcp_f32_e32 v169, v151
	v_mul_f32_e32 v151, 0xbfb8aa3b, v170
	v_exp_f32_e32 v151, v151
	v_pk_mul_f32 v[168:169], v[162:163], v[168:169]
	v_pk_mul_f32 v[162:163], v[46:47], v[166:167] op_sel_hi:[1,0]
	v_add_f32_e32 v151, 1.0, v151
	v_rcp_f32_e32 v172, v151
	v_mul_f32_e32 v151, 0xbfb8aa3b, v171
	v_exp_f32_e32 v151, v151
	s_nop 0
	v_add_f32_e32 v151, 1.0, v151
	v_rcp_f32_e32 v173, v151
	v_mul_f32_e32 v151, 0xbfb8aa3b, v162
	v_exp_f32_e32 v151, v151
	v_pk_mul_f32 v[170:171], v[170:171], v[172:173]
	v_add_f32_e32 v151, 1.0, v151
	v_rcp_f32_e32 v172, v151
	v_mul_f32_e32 v151, 0xbfb8aa3b, v163
	v_exp_f32_e32 v151, v151
	s_nop 0
	v_add_f32_e32 v151, 1.0, v151
	v_rcp_f32_e32 v173, v151
	s_nop 0
	v_pk_mul_f32 v[172:173], v[162:163], v[172:173]
	v_cvt_pk_bf16_f32 v163, v168, v169
	v_add_co_u32_e32 v168, vcc, s0, v132
	v_cvt_pk_bf16_f32 v162, v164, v165
	v_cvt_pk_bf16_f32 v164, v170, v171
	v_cvt_pk_bf16_f32 v165, v172, v173
	v_addc_co_u32_e32 v169, vcc, 0, v133, vcc
	global_store_dwordx4 v[168:169], v[162:165], off
	s_mov_b64 s[0:1], 0x50000
	s_nop 0
	v_pk_mul_f32 v[162:163], v[40:41], v[166:167] op_sel_hi:[1,0]
	v_pk_mul_f32 v[164:165], v[42:43], v[166:167] op_sel_hi:[1,0]
	v_mul_f32_e32 v151, 0xbfb8aa3b, v162
	v_exp_f32_e32 v151, v151
	s_nop 0
	v_add_f32_e32 v151, 1.0, v151
	v_rcp_f32_e32 v168, v151
	v_mul_f32_e32 v151, 0xbfb8aa3b, v163
	v_exp_f32_e32 v151, v151
	s_nop 0
	v_add_f32_e32 v151, 1.0, v151
	v_rcp_f32_e32 v169, v151
	v_mul_f32_e32 v151, 0xbfb8aa3b, v164
	v_exp_f32_e32 v151, v151
	v_pk_mul_f32 v[162:163], v[162:163], v[168:169]
	s_nop 0
	v_cvt_pk_bf16_f32 v162, v162, v163
	v_add_f32_e32 v151, 1.0, v151
	v_rcp_f32_e32 v168, v151
	v_mul_f32_e32 v151, 0xbfb8aa3b, v165
	v_exp_f32_e32 v151, v151
	s_nop 0
	v_add_f32_e32 v151, 1.0, v151
	v_rcp_f32_e32 v169, v151
	s_nop 0
	v_pk_mul_f32 v[164:165], v[164:165], v[168:169]
	v_pk_mul_f32 v[168:169], v[38:39], v[166:167] op_sel_hi:[1,0]
	v_pk_mul_f32 v[166:167], v[36:37], v[166:167] op_sel_hi:[1,0]
	v_cvt_pk_bf16_f32 v163, v164, v165
	v_mul_f32_e32 v151, 0xbfb8aa3b, v166
	v_exp_f32_e32 v151, v151
	s_nop 0
	v_add_f32_e32 v151, 1.0, v151
	v_rcp_f32_e32 v170, v151
	v_mul_f32_e32 v151, 0xbfb8aa3b, v167
	v_exp_f32_e32 v151, v151
	s_nop 0
	v_add_f32_e32 v151, 1.0, v151
	v_rcp_f32_e32 v171, v151
	v_mul_f32_e32 v151, 0xbfb8aa3b, v168
	v_exp_f32_e32 v151, v151
	v_pk_mul_f32 v[166:167], v[166:167], v[170:171]
	s_nop 0
	v_cvt_pk_bf16_f32 v164, v166, v167
	v_add_f32_e32 v151, 1.0, v151
	v_rcp_f32_e32 v170, v151
	v_mul_f32_e32 v151, 0xbfb8aa3b, v169
	v_exp_f32_e32 v151, v151
	s_nop 0
	v_add_f32_e32 v151, 1.0, v151
	v_rcp_f32_e32 v171, v151
	s_nop 0
	v_pk_mul_f32 v[168:169], v[168:169], v[170:171]
	s_nop 0
	v_cvt_pk_bf16_f32 v165, v168, v169
	global_store_dwordx4 v[160:161], v[162:165], off offset:256
	s_nop 1
	v_mov_b32_e32 v166, v249
	v_lshl_add_u64 v[160:161], v[132:133], 0, s[0:1]
	s_mov_b32 s0, 0x50000
	v_pk_mul_f32 v[164:165], v[32:33], v[166:167] op_sel_hi:[1,0]
	s_nop 0
	v_mul_f32_e32 v151, 0xbfb8aa3b, v164
	v_exp_f32_e32 v151, v151
	v_pk_mul_f32 v[162:163], v[34:35], v[166:167] op_sel_hi:[1,0]
	v_pk_mul_f32 v[170:171], v[28:29], v[166:167] op_sel_hi:[1,0]
	v_add_f32_e32 v151, 1.0, v151
	v_rcp_f32_e32 v168, v151
	v_mul_f32_e32 v151, 0xbfb8aa3b, v165
	v_exp_f32_e32 v151, v151
	s_nop 0
	v_add_f32_e32 v151, 1.0, v151
	v_rcp_f32_e32 v169, v151
	v_mul_f32_e32 v151, 0xbfb8aa3b, v162
	v_exp_f32_e32 v151, v151
	v_pk_mul_f32 v[164:165], v[164:165], v[168:169]
	v_add_f32_e32 v151, 1.0, v151
	v_rcp_f32_e32 v168, v151
	v_mul_f32_e32 v151, 0xbfb8aa3b, v163
	v_exp_f32_e32 v151, v151
	s_nop 0
	v_add_f32_e32 v151, 1.0, v151
	v_rcp_f32_e32 v169, v151
	v_mul_f32_e32 v151, 0xbfb8aa3b, v170
	v_exp_f32_e32 v151, v151
	v_pk_mul_f32 v[168:169], v[162:163], v[168:169]
	v_pk_mul_f32 v[162:163], v[30:31], v[166:167] op_sel_hi:[1,0]
	v_add_f32_e32 v151, 1.0, v151
	v_rcp_f32_e32 v172, v151
	v_mul_f32_e32 v151, 0xbfb8aa3b, v171
	v_exp_f32_e32 v151, v151
	s_nop 0
	v_add_f32_e32 v151, 1.0, v151
	v_rcp_f32_e32 v173, v151
	v_mul_f32_e32 v151, 0xbfb8aa3b, v162
	v_exp_f32_e32 v151, v151
	v_pk_mul_f32 v[170:171], v[170:171], v[172:173]
	v_add_f32_e32 v151, 1.0, v151
	v_rcp_f32_e32 v172, v151
	v_mul_f32_e32 v151, 0xbfb8aa3b, v163
	v_exp_f32_e32 v151, v151
	s_nop 0
	v_add_f32_e32 v151, 1.0, v151
	v_rcp_f32_e32 v173, v151
	s_nop 0
	v_pk_mul_f32 v[172:173], v[162:163], v[172:173]
	v_cvt_pk_bf16_f32 v163, v168, v169
	v_add_co_u32_e32 v168, vcc, s0, v132
	v_cvt_pk_bf16_f32 v162, v164, v165
	v_cvt_pk_bf16_f32 v164, v170, v171
	v_cvt_pk_bf16_f32 v165, v172, v173
	v_addc_co_u32_e32 v169, vcc, 0, v133, vcc
	global_store_dwordx4 v[168:169], v[162:165], off
	s_mov_b64 s[0:1], 0x58000
	s_nop 0
	v_pk_mul_f32 v[162:163], v[24:25], v[166:167] op_sel_hi:[1,0]
	v_pk_mul_f32 v[164:165], v[26:27], v[166:167] op_sel_hi:[1,0]
	v_mul_f32_e32 v151, 0xbfb8aa3b, v162
	v_exp_f32_e32 v151, v151
	s_nop 0
	v_add_f32_e32 v151, 1.0, v151
	v_rcp_f32_e32 v168, v151
	v_mul_f32_e32 v151, 0xbfb8aa3b, v163
	v_exp_f32_e32 v151, v151
	s_nop 0
	v_add_f32_e32 v151, 1.0, v151
	v_rcp_f32_e32 v169, v151
	v_mul_f32_e32 v151, 0xbfb8aa3b, v164
	v_exp_f32_e32 v151, v151
	v_pk_mul_f32 v[162:163], v[162:163], v[168:169]
	s_nop 0
	v_cvt_pk_bf16_f32 v162, v162, v163
	v_add_f32_e32 v151, 1.0, v151
	v_rcp_f32_e32 v168, v151
	v_mul_f32_e32 v151, 0xbfb8aa3b, v165
	v_exp_f32_e32 v151, v151
	s_nop 0
	v_add_f32_e32 v151, 1.0, v151
	v_rcp_f32_e32 v169, v151
	s_nop 0
	v_pk_mul_f32 v[164:165], v[164:165], v[168:169]
	v_pk_mul_f32 v[168:169], v[22:23], v[166:167] op_sel_hi:[1,0]
	v_pk_mul_f32 v[166:167], v[20:21], v[166:167] op_sel_hi:[1,0]
	v_cvt_pk_bf16_f32 v163, v164, v165
	v_mul_f32_e32 v151, 0xbfb8aa3b, v166
	v_exp_f32_e32 v151, v151
	s_nop 0
	v_add_f32_e32 v151, 1.0, v151
	v_rcp_f32_e32 v170, v151
	v_mul_f32_e32 v151, 0xbfb8aa3b, v167
	v_exp_f32_e32 v151, v151
	s_nop 0
	v_add_f32_e32 v151, 1.0, v151
	v_rcp_f32_e32 v171, v151
	v_mul_f32_e32 v151, 0xbfb8aa3b, v168
	v_exp_f32_e32 v151, v151
	v_pk_mul_f32 v[166:167], v[166:167], v[170:171]
	s_nop 0
	v_cvt_pk_bf16_f32 v164, v166, v167
	v_add_f32_e32 v151, 1.0, v151
	v_rcp_f32_e32 v170, v151
	v_mul_f32_e32 v151, 0xbfb8aa3b, v169
	v_exp_f32_e32 v151, v151
	s_nop 0
	v_add_f32_e32 v151, 1.0, v151
	v_rcp_f32_e32 v171, v151
	s_nop 0
	v_pk_mul_f32 v[168:169], v[168:169], v[170:171]
	s_nop 0
	v_cvt_pk_bf16_f32 v165, v168, v169
	global_store_dwordx4 v[160:161], v[162:165], off offset:256
	s_nop 1
	v_mov_b32_e32 v164, v250
	v_lshl_add_u64 v[134:135], v[132:133], 0, s[0:1]
	s_mov_b32 s0, 0x58000
	v_add_co_u32_e32 v132, vcc, s0, v132
	s_nop 1
	v_addc_co_u32_e32 v133, vcc, 0, v133, vcc
	v_pk_mul_f32 v[162:163], v[16:17], v[164:165] op_sel_hi:[1,0]
	s_nop 0
	v_mul_f32_e32 v151, 0xbfb8aa3b, v162
	v_exp_f32_e32 v151, v151
	v_pk_mul_f32 v[160:161], v[18:19], v[164:165] op_sel_hi:[1,0]
	v_pk_mul_f32 v[168:169], v[12:13], v[164:165] op_sel_hi:[1,0]
	v_add_f32_e32 v151, 1.0, v151
	v_rcp_f32_e32 v166, v151
	v_mul_f32_e32 v151, 0xbfb8aa3b, v163
	v_exp_f32_e32 v151, v151
	s_nop 0
	v_add_f32_e32 v151, 1.0, v151
	v_rcp_f32_e32 v167, v151
	v_mul_f32_e32 v151, 0xbfb8aa3b, v160
	v_exp_f32_e32 v151, v151
	v_pk_mul_f32 v[162:163], v[162:163], v[166:167]
	v_add_f32_e32 v151, 1.0, v151
	v_rcp_f32_e32 v166, v151
	v_mul_f32_e32 v151, 0xbfb8aa3b, v161
	v_exp_f32_e32 v151, v151
	s_nop 0
	v_add_f32_e32 v151, 1.0, v151
	v_rcp_f32_e32 v167, v151
	v_mul_f32_e32 v151, 0xbfb8aa3b, v168
	v_exp_f32_e32 v151, v151
	v_pk_mul_f32 v[166:167], v[160:161], v[166:167]
	v_pk_mul_f32 v[160:161], v[14:15], v[164:165] op_sel_hi:[1,0]
	v_add_f32_e32 v151, 1.0, v151
	v_rcp_f32_e32 v170, v151
	v_mul_f32_e32 v151, 0xbfb8aa3b, v169
	v_exp_f32_e32 v151, v151
	s_nop 0
	v_add_f32_e32 v151, 1.0, v151
	v_rcp_f32_e32 v171, v151
	v_mul_f32_e32 v151, 0xbfb8aa3b, v160
	v_exp_f32_e32 v151, v151
	v_pk_mul_f32 v[168:169], v[168:169], v[170:171]
	v_add_f32_e32 v151, 1.0, v151
	v_rcp_f32_e32 v170, v151
	v_mul_f32_e32 v151, 0xbfb8aa3b, v161
	v_exp_f32_e32 v151, v151
	s_nop 0
	v_add_f32_e32 v151, 1.0, v151
	v_rcp_f32_e32 v171, v151
	s_nop 0
	v_pk_mul_f32 v[170:171], v[160:161], v[170:171]
	v_cvt_pk_bf16_f32 v160, v162, v163
	v_cvt_pk_bf16_f32 v161, v166, v167
	v_cvt_pk_bf16_f32 v162, v168, v169
	v_cvt_pk_bf16_f32 v163, v170, v171
	global_store_dwordx4 v[132:133], v[160:163], off
	v_pk_mul_f32 v[132:133], v[8:9], v[164:165] op_sel_hi:[1,0]
	s_nop 0
	v_mul_f32_e32 v151, 0xbfb8aa3b, v132
	v_exp_f32_e32 v151, v151
	v_pk_mul_f32 v[160:161], v[10:11], v[164:165] op_sel_hi:[1,0]
	v_add_f32_e32 v151, 1.0, v151
	v_rcp_f32_e32 v162, v151
	v_mul_f32_e32 v151, 0xbfb8aa3b, v133
	v_exp_f32_e32 v151, v151
	s_nop 0
	v_add_f32_e32 v151, 1.0, v151
	v_rcp_f32_e32 v163, v151
	v_mul_f32_e32 v151, 0xbfb8aa3b, v160
	v_exp_f32_e32 v151, v151
	v_pk_mul_f32 v[132:133], v[132:133], v[162:163]
	v_add_f32_e32 v151, 1.0, v151
	v_rcp_f32_e32 v162, v151
	v_mul_f32_e32 v151, 0xbfb8aa3b, v161
	v_exp_f32_e32 v151, v151
	s_nop 0
	v_add_f32_e32 v151, 1.0, v151
	v_rcp_f32_e32 v163, v151
	s_nop 0
	v_pk_mul_f32 v[160:161], v[160:161], v[162:163]
	v_pk_mul_f32 v[162:163], v[6:7], v[164:165] op_sel_hi:[1,0]
	v_pk_mul_f32 v[164:165], v[4:5], v[164:165] op_sel_hi:[1,0]
	s_nop 0
	v_mul_f32_e32 v151, 0xbfb8aa3b, v164
	v_exp_f32_e32 v151, v151
	s_nop 0
	v_add_f32_e32 v151, 1.0, v151
	v_rcp_f32_e32 v166, v151
	v_mul_f32_e32 v151, 0xbfb8aa3b, v165
	v_exp_f32_e32 v151, v151
	s_nop 0
	v_add_f32_e32 v151, 1.0, v151
	v_rcp_f32_e32 v167, v151
	v_mul_f32_e32 v151, 0xbfb8aa3b, v162
	v_exp_f32_e32 v151, v151
	v_pk_mul_f32 v[164:165], v[164:165], v[166:167]
	s_nop 0
	v_cvt_pk_bf16_f32 v164, v164, v165
	v_add_f32_e32 v151, 1.0, v151
	v_rcp_f32_e32 v166, v151
	v_mul_f32_e32 v151, 0xbfb8aa3b, v163
	v_exp_f32_e32 v151, v151
	s_nop 0
	v_add_f32_e32 v151, 1.0, v151
	v_rcp_f32_e32 v167, v151
	s_nop 0
	v_pk_mul_f32 v[166:167], v[162:163], v[166:167]
	v_cvt_pk_bf16_f32 v162, v132, v133
	v_cvt_pk_bf16_f32 v163, v160, v161
	v_cvt_pk_bf16_f32 v165, v166, v167
	global_store_dwordx4 v[134:135], v[162:165], off offset:256
	s_cbranch_execnz .LBB0_161
